# attention phase load balance: the 8 CUs with a third pool_up tile hand their two shortest attention units (R0=128) to 16 other CUs as a fifth unit (second attempt after a replayer abort)
# speedup vs baseline: 1.0054x; 1.0023x over previous
; __device__ __forceinline__ void phase_attn(const Args& a, int l, LAS unsigned char* lds, int vcu, int G, int wv) {
;     ...
;     { const float* gq = a.qn_gain + (size_t)l * 96; const float* gk = a.kn_gain + (size_t)l * 96;
;       float mq = 0.f, mk = 0.f;
;       for (int i = 0; i < 96; ++i) { mq = fmaxf(mq, fabsf(gq[i])); mk = fmaxf(mk, fabsf(gk[i])); }
;       kb = 1.01f * 9.7979590f * mk;
;       const float hi = kb * 9.7979590f * mq * QSCALE;
;       if (!(hi < 48.f)) kb = -1.f; }
;     const int sp0 = (G == 256) ? ((vcu >= 33 && vcu < 64) ? vcu - 33 : (vcu == 65 ? 31 : -1)) : (vcu < 32 ? vcu : -1);
;     const int nmain = (vcu < 512) ? 2 * ((512 - vcu + G - 1) / G) : 0, nspec = (G == 256) ? (sp0 >= 0 ? 1 : 0) : ((vcu < 32) ? (32 - vcu + G - 1) / G : 0);
;     ...
;     const int nun = nmain + nspec;
.LBB0_23:
	s_add_i32 s13, s0, s12
	s_mov_b32 s100, 1
	s_mov_b32 s101, 0
	s_cmpk_lg_i32 s33, 0x100
	s_cbranch_scc1 .Lfa_nobal
	s_and_b32 s0, s83, 31
	s_cmp_eq_u32 s0, 0
	s_cselect_b32 s100, 0, 1
	s_cselect_b32 s12, 2, s12
	s_cselect_b32 s13, 2, s13
	s_sub_i32 s0, s83, 0x42
	s_cmp_lt_u32 s0, 16
	s_cbranch_scc0 .Lfa_nobal
	s_lshl_b32 s0, s0, 1
	s_movk_i32 s101, 0x80
	s_add_i32 s13, s13, 1
	v_writelane_b32 v252, s0, 6
.Lfa_nobal:
	s_cmp_lt_i32 s13, 1
	s_cbranch_scc1 .LBB0_214
	v_mul_f32_e32 v2, 0x411e55c4, v2
	v_mul_f32_e32 v3, 0x411cc471, v2
	v_mul_f32_e32 v0, v0, v3
	v_mul_f32_e32 v0, 0x3e16c740, v0
	s_mov_b32 s0, 0x42400000
	v_cmp_gt_f32_e32 vcc, s0, v0
	v_readlane_b32 s0, v254, 45
	v_readlane_b32 s1, v254, 46
	s_mov_b32 s2, s0
	s_mul_i32 s1, s2, 0x180
	v_readlane_b32 s2, v254, 41
	v_readlane_b32 s3, v254, 42
	s_add_u32 s14, s2, 0x2200000
	s_addc_u32 s15, s3, 0
	s_add_u32 s46, s2, 0x1300000
	s_addc_u32 s47, s3, 0
	s_add_u32 s50, s2, 0x18800000
	s_addc_u32 s51, s3, 0
	s_add_u32 s52, s2, 0x1b900000
	v_readlane_b32 s56, v253, 40
	s_addc_u32 s53, s3, 0
	v_readlane_b32 s57, v253, 41
	v_readlane_b32 s58, v253, 42
	v_readlane_b32 s59, v253, 43
	v_readlane_b32 s60, v253, 44
	v_readlane_b32 s61, v253, 45
	v_readlane_b32 s62, v253, 46
	v_readlane_b32 s63, v253, 47
	v_readlane_b32 s64, v253, 48
	v_readlane_b32 s65, v253, 49
	v_readlane_b32 s66, v253, 50
	v_readlane_b32 s67, v253, 51
	s_add_u32 s2, s2, 0x6300000
	v_readlane_b32 s68, v253, 52
	v_readlane_b32 s69, v253, 53
	v_readlane_b32 s70, v253, 54
	v_readlane_b32 s71, v253, 55
	s_mov_b64 s[56:57], s[60:61]
	s_addc_u32 s3, s3, 0
	s_mov_b64 s[58:59], s[62:63]
	s_mov_b64 s[60:61], s[64:65]
	s_mul_hi_i32 s0, s0, 0x180
	s_add_u32 s4, s60, s1
	s_addc_u32 s5, s61, s0
	v_readlane_b32 s0, v253, 33
	v_cndmask_b32_e32 v178, -1.0, v2, vcc
	s_add_u32 s54, s0, s92
	v_readlane_b32 s0, v253, 34
	v_cmp_lt_f32_e64 s[36:37], 0, v178
	v_cmp_nlt_f32_e64 s[38:39], 0, v178
	s_addc_u32 s55, s0, s93
	s_mov_b32 s20, 0
	s_mov_b64 s[62:63], s[66:67]
	s_mov_b64 s[64:65], s[68:69]
	s_mov_b64 s[66:67], s[70:71]
	s_branch .LBB0_26

; #define ATT_UNIT_PARAMS(j, B_, H_, R_, S_) do { if ((j) < nmain) { const int it = vcu + ((j) >> 1) * G, bh = it >> 4, s_ = it & 15; B_ = bh >> 3; H_ = bh & 7; R_ = 128 + 256 * (((j) & 1) ? s_ : 31 - s_); S_ = false; } \
;         else { const int it = (G == 256) ? sp0 : vcu + ((j) - nmain) * G; B_ = it >> 3; H_ = it & 7; R_ = 0; S_ = true; } } while (0)
; __device__ __forceinline__ void phase_attn(const Args& a, int l, LAS unsigned char* lds, int vcu, int G, int wv) {
;     ...
;     const int nun = nmain + nspec;
;     for (int j = 0; j < nun; ++j) {
;         int b, h, R0, nb = 0, nh = 0, nR0 = 0; bool special, nsp = false;
;         ATT_UNIT_PARAMS(j, b, h, R0, special);
;         const bool hasn = j + 1 < nun;
;         if (hasn) ATT_UNIT_PARAMS(j + 1, nb, nh, nR0, nsp);
;         attn_unit(a, l, b, h, R0, special, lds, kb, wv, j > 0, hasn, nb, nh, nR0);
.LBB0_26:
	s_cmp_ge_i32 s20, s12
	s_cselect_b64 s[16:17], -1, 0
	s_mov_b64 s[0:1], -1
	s_and_b64 vcc, exec, s[16:17]
	s_cbranch_vccnz .LBB0_28
	s_lshr_b32 s0, s20, s100
	s_mul_i32 s0, s0, s33
	s_add_i32 s0, s0, s83
	s_lshr_b32 s18, s0, 4
	s_ashr_i32 s40, s0, 7
	s_lshl_b32 s0, s0, 8
	s_and_b32 s0, s0, 0xf00
	s_and_b32 s1, s20, s100
	s_xor_b32 s6, s0, 0x1f00
	s_cmp_eq_u32 s1, 0
	s_cselect_b32 s0, s6, s0
	s_or_b32 s44, s0, 0x80
	s_mov_b64 s[0:1], 0
.LBB0_28:
	s_andn2_b64 vcc, exec, s[0:1]
	s_cbranch_vccnz .LBB0_30
	s_sub_i32 s0, s20, s12
	s_mul_i32 s0, s0, s33
	s_add_i32 s6, s0, s83
	v_readlane_b32 s0, v253, 24
	v_readlane_b32 s1, v253, 25
	s_and_b64 s[0:1], s[0:1], exec
	v_readlane_b32 s0, v252, 6
	s_cselect_b32 s18, s0, s6
	s_ashr_i32 s40, s18, 3
	s_mov_b32 s44, s101
	s_cmp_eq_u32 s101, 0
	s_cselect_b64 s[16:17], s[16:17], 0
.LBB0_30:
	s_add_i32 s56, s20, 1
	s_cmp_lt_i32 s56, s13
	s_mov_b32 s58, 0
	s_cselect_b64 s[6:7], -1, 0
	s_cmp_ge_i32 s56, s13
	s_mov_b32 s62, 0
	s_mov_b32 s57, 0
	s_cbranch_scc1 .LBB0_35
	s_cmp_ge_i32 s56, s12
	s_mov_b64 s[0:1], -1
	s_cbranch_scc0 .LBB0_33
	s_sub_i32 s0, s56, s12
	s_mul_i32 s0, s0, s33
	s_add_i32 s19, s0, s83
	v_readlane_b32 s0, v253, 24
	v_readlane_b32 s1, v253, 25
	s_and_b64 s[0:1], s[0:1], exec
	v_readlane_b32 s0, v252, 6
	s_cselect_b32 s0, s0, s19
	s_ashr_i32 s57, s0, 3
	s_and_b32 s58, s0, 7
	s_mov_b32 s62, s101
	s_mov_b64 s[0:1], 0
.LBB0_33:
	s_andn2_b64 vcc, exec, s[0:1]
	s_cbranch_vccnz .LBB0_35
	s_lshr_b32 s0, s56, s100
	s_mul_i32 s0, s0, s33
	s_add_i32 s0, s0, s83
	s_ashr_i32 s57, s0, 7
	s_bfe_u32 s58, s0, 0x30004
	s_lshl_b32 s0, s0, 8
	s_and_b32 s0, s0, 0xf00
	s_xor_b32 s1, s100, 1
	s_or_b32 s1, s1, s20
	s_and_b32 s1, s1, 1
	s_xor_b32 s19, s0, 0x1f00
	s_cmp_eq_u32 s1, 0
	s_cselect_b32 s0, s0, s19
	s_or_b32 s62, s0, 0x80
